# as v18 plus scan pass 1 inner loop rewritten: the 16 loads of each 8-row batch issued together with counted vmcnt waits
# speedup vs baseline: 1.0059x; 1.0059x over previous
; __device__ __forceinline__ float bf_lo(unsigned w) { return __uint_as_float(w << 16); }
; __device__ __forceinline__ float bf_hi(unsigned w) { return __uint_as_float(w & 0xffff0000u); }
; __global__ void __launch_bounds__(NTHREADS) mk_fwd(Params P) {
;     ...
;                     for (int it = gt; it < 512 * 512; it += NGT) { const int ch = it >> 9, cp = it & 511, col = cp * 2; const bool bwd = col >= 512;
;                         const size_t base = (size_t)ch * 64 * 1024 + col;
;                         float h0 = 0.f, h1 = 0.f, s0 = 0.f, s1 = 0.f;
; #pragma unroll 8
;                         for (int i = 0; i < 64; ++i) { const int tt = bwd ? 63 - i : i; const unsigned lw = *(const unsigned*)(LA + base + (size_t)tt * 1024), uw = *(const unsigned*)(U + base + (size_t)tt * 1024);
;                             const float l0 = bf_lo(lw), l1 = bf_hi(lw); s0 += l0; s1 += l1;
;                             h0 = __builtin_amdgcn_exp2f(l0) * h0 + bf_lo(uw); h1 = __builtin_amdgcn_exp2f(l1) * h1 + bf_hi(uw); }
;                         *(f32x2*)(aggP + (size_t)ch * 1024 + col) = (f32x2){__builtin_amdgcn_exp2f(s0), __builtin_amdgcn_exp2f(s1)};
;                         *(f32x2*)(aggH + (size_t)ch * 1024 + col) = (f32x2){h0, h1}; }
.LBB0_1165:
	s_add_i32 s0, s24, 7
	s_add_i32 s1, s23, 0
	v_mov_b32_e32 v12, s1
	v_mov_b32_e32 v13, s0
	v_cndmask_b32_e32 v12, v12, v13, vcc
	v_lshlrev_b32_e32 v80, 11, v12
	v_lshl_add_u64 v[12:13], v[4:5], 0, v[80:81]
	global_load_dword v20, v[12:13], off
	v_lshl_add_u64 v[12:13], v[6:7], 0, v[80:81]
	global_load_dword v21, v[12:13], off
	s_add_i32 s0, s24, 6
	s_add_i32 s1, s23, 1
	v_mov_b32_e32 v12, s1
	v_mov_b32_e32 v13, s0
	v_cndmask_b32_e32 v12, v12, v13, vcc
	v_lshlrev_b32_e32 v80, 11, v12
	v_lshl_add_u64 v[12:13], v[4:5], 0, v[80:81]
	global_load_dword v22, v[12:13], off
	v_lshl_add_u64 v[12:13], v[6:7], 0, v[80:81]
	global_load_dword v23, v[12:13], off
	s_add_i32 s0, s24, 5
	s_add_i32 s1, s23, 2
	v_mov_b32_e32 v12, s1
	v_mov_b32_e32 v13, s0
	v_cndmask_b32_e32 v12, v12, v13, vcc
	v_lshlrev_b32_e32 v80, 11, v12
	v_lshl_add_u64 v[12:13], v[4:5], 0, v[80:81]
	global_load_dword v24, v[12:13], off
	v_lshl_add_u64 v[12:13], v[6:7], 0, v[80:81]
	global_load_dword v25, v[12:13], off
	s_add_i32 s0, s24, 4
	s_add_i32 s1, s23, 3
	v_mov_b32_e32 v12, s1
	v_mov_b32_e32 v13, s0
	v_cndmask_b32_e32 v12, v12, v13, vcc
	v_lshlrev_b32_e32 v80, 11, v12
	v_lshl_add_u64 v[12:13], v[4:5], 0, v[80:81]
	global_load_dword v26, v[12:13], off
	v_lshl_add_u64 v[12:13], v[6:7], 0, v[80:81]
	global_load_dword v27, v[12:13], off
	s_add_i32 s0, s24, 3
	s_add_i32 s1, s23, 4
	v_mov_b32_e32 v12, s1
	v_mov_b32_e32 v13, s0
	v_cndmask_b32_e32 v12, v12, v13, vcc
	v_lshlrev_b32_e32 v80, 11, v12
	v_lshl_add_u64 v[12:13], v[4:5], 0, v[80:81]
	global_load_dword v28, v[12:13], off
	v_lshl_add_u64 v[12:13], v[6:7], 0, v[80:81]
	global_load_dword v29, v[12:13], off
	s_add_i32 s0, s24, 2
	s_add_i32 s1, s23, 5
	v_mov_b32_e32 v12, s1
	v_mov_b32_e32 v13, s0
	v_cndmask_b32_e32 v12, v12, v13, vcc
	v_lshlrev_b32_e32 v80, 11, v12
	v_lshl_add_u64 v[12:13], v[4:5], 0, v[80:81]
	global_load_dword v30, v[12:13], off
	v_lshl_add_u64 v[12:13], v[6:7], 0, v[80:81]
	global_load_dword v31, v[12:13], off
	s_add_i32 s0, s24, 1
	s_add_i32 s1, s23, 6
	v_mov_b32_e32 v12, s1
	v_mov_b32_e32 v13, s0
	v_cndmask_b32_e32 v12, v12, v13, vcc
	v_lshlrev_b32_e32 v80, 11, v12
	v_lshl_add_u64 v[12:13], v[4:5], 0, v[80:81]
	global_load_dword v32, v[12:13], off
	v_lshl_add_u64 v[12:13], v[6:7], 0, v[80:81]
	global_load_dword v33, v[12:13], off
	s_add_i32 s0, s24, 0
	s_add_i32 s1, s23, 7
	v_mov_b32_e32 v12, s1
	v_mov_b32_e32 v13, s0
	v_cndmask_b32_e32 v12, v12, v13, vcc
	v_lshlrev_b32_e32 v80, 11, v12
	v_lshl_add_u64 v[12:13], v[4:5], 0, v[80:81]
	global_load_dword v34, v[12:13], off
	v_lshl_add_u64 v[12:13], v[6:7], 0, v[80:81]
	global_load_dword v35, v[12:13], off
	s_add_i32 s23, s23, 8
	s_add_i32 s24, s24, -8
	s_cmp_eq_u32 s23, 64
	s_waitcnt vmcnt(14)
	v_lshlrev_b32_e32 v12, 16, v20
	v_and_b32_e32 v13, 0xffff0000, v20
	v_pk_add_f32 v[10:11], v[10:11], v[12:13]
	v_exp_f32_e32 v12, v12
	v_exp_f32_e32 v13, v13
	v_lshlrev_b32_e32 v14, 16, v21
	v_and_b32_e32 v15, 0xffff0000, v21
	v_pk_fma_f32 v[8:9], v[8:9], v[12:13], v[14:15]
	s_waitcnt vmcnt(12)
	v_lshlrev_b32_e32 v12, 16, v22
	v_and_b32_e32 v13, 0xffff0000, v22
	v_pk_add_f32 v[10:11], v[10:11], v[12:13]
	v_exp_f32_e32 v12, v12
	v_exp_f32_e32 v13, v13
	v_lshlrev_b32_e32 v14, 16, v23
	v_and_b32_e32 v15, 0xffff0000, v23
	v_pk_fma_f32 v[8:9], v[8:9], v[12:13], v[14:15]
	s_waitcnt vmcnt(10)
	v_lshlrev_b32_e32 v12, 16, v24
	v_and_b32_e32 v13, 0xffff0000, v24
	v_pk_add_f32 v[10:11], v[10:11], v[12:13]
	v_exp_f32_e32 v12, v12
	v_exp_f32_e32 v13, v13
	v_lshlrev_b32_e32 v14, 16, v25
	v_and_b32_e32 v15, 0xffff0000, v25
	v_pk_fma_f32 v[8:9], v[8:9], v[12:13], v[14:15]
	s_waitcnt vmcnt(8)
	v_lshlrev_b32_e32 v12, 16, v26
	v_and_b32_e32 v13, 0xffff0000, v26
	v_pk_add_f32 v[10:11], v[10:11], v[12:13]
	v_exp_f32_e32 v12, v12
	v_exp_f32_e32 v13, v13
	v_lshlrev_b32_e32 v14, 16, v27
	v_and_b32_e32 v15, 0xffff0000, v27
	v_pk_fma_f32 v[8:9], v[8:9], v[12:13], v[14:15]
	s_waitcnt vmcnt(6)
	v_lshlrev_b32_e32 v12, 16, v28
	v_and_b32_e32 v13, 0xffff0000, v28
	v_pk_add_f32 v[10:11], v[10:11], v[12:13]
	v_exp_f32_e32 v12, v12
	v_exp_f32_e32 v13, v13
	v_lshlrev_b32_e32 v14, 16, v29
	v_and_b32_e32 v15, 0xffff0000, v29
	v_pk_fma_f32 v[8:9], v[8:9], v[12:13], v[14:15]
	s_waitcnt vmcnt(4)
	v_lshlrev_b32_e32 v12, 16, v30
	v_and_b32_e32 v13, 0xffff0000, v30
	v_pk_add_f32 v[10:11], v[10:11], v[12:13]
	v_exp_f32_e32 v12, v12
	v_exp_f32_e32 v13, v13
	v_lshlrev_b32_e32 v14, 16, v31
	v_and_b32_e32 v15, 0xffff0000, v31
	v_pk_fma_f32 v[8:9], v[8:9], v[12:13], v[14:15]
	s_waitcnt vmcnt(2)
	v_lshlrev_b32_e32 v12, 16, v32
	v_and_b32_e32 v13, 0xffff0000, v32
	v_pk_add_f32 v[10:11], v[10:11], v[12:13]
	v_exp_f32_e32 v12, v12
	v_exp_f32_e32 v13, v13
	v_lshlrev_b32_e32 v14, 16, v33
	v_and_b32_e32 v15, 0xffff0000, v33
	v_pk_fma_f32 v[8:9], v[8:9], v[12:13], v[14:15]
	s_waitcnt vmcnt(0)
	v_lshlrev_b32_e32 v12, 16, v34
	v_and_b32_e32 v13, 0xffff0000, v34
	v_pk_add_f32 v[10:11], v[10:11], v[12:13]
	v_exp_f32_e32 v12, v12
	v_exp_f32_e32 v13, v13
	v_lshlrev_b32_e32 v14, 16, v35
	v_and_b32_e32 v15, 0xffff0000, v35
	v_pk_fma_f32 v[8:9], v[8:9], v[12:13], v[14:15]
	s_cbranch_scc0 .LBB0_1165
	v_exp_f32_e32 v4, v10
	v_exp_f32_e32 v5, v11
	v_lshlrev_b64 v[0:1], 12, v[0:1]
	v_add_u32_e32 v3, s82, v3
	s_mov_b32 s0, 0x3ffff
	v_lshl_add_u64 v[6:7], s[96:97], 0, v[0:1]
	v_lshlrev_b32_e32 v80, 2, v2
	v_lshl_add_u64 v[0:1], s[38:39], 0, v[0:1]
	v_cmp_lt_i32_e32 vcc, s0, v3
	v_lshl_add_u64 v[6:7], v[6:7], 0, v[80:81]
	v_lshl_add_u64 v[0:1], v[0:1], 0, v[80:81]
	s_or_b64 s[42:43], vcc, s[42:43]
	global_store_dwordx2 v[6:7], v[4:5], off
	global_store_dwordx2 v[0:1], v[8:9], off
	s_andn2_b64 exec, exec, s[42:43]
	s_cbranch_execnz .LBB0_1164
